# P1 proj: first half of the unit epilogue (ai=0 row blocks: rstd scale, bf16 pack, stores) interleaved into the last MFMA block of the unit; on fast seam + rstd LDS table
# speedup vs baseline: 1.0049x; 1.0022x over previous
.LBB0_111:
	s_add_u32 s72, vcc_lo, 0xffea0080
	s_addc_u32 s73, vcc_hi, -1
	s_add_i32 s95, 0, 0x10000
	s_cmp_eq_u32 s93, 12
	s_cselect_b32 s79, s1, s73
	s_cselect_b32 s78, s0, s72
	v_add_u32_e32 v26, s95, v186
	s_cselect_b32 s77, s89, s85
	s_cselect_b32 s76, s88, s84
	s_add_i32 s12, 0, 0x14000
	ds_read_b128 v[36:39], v26
	ds_read_b128 v[56:59], v26 offset:1024
	ds_read_b128 v[84:87], v26 offset:2048
	ds_read_b128 v[104:107], v26 offset:3072
	v_add_u32_e32 v26, s12, v186
	ds_read_b128 v[124:127], v26
	ds_read_b128 v[144:147], v26 offset:1024
	ds_read_b128 v[156:159], v26 offset:2048
	ds_read_b128 v[180:183], v26 offset:3072
	v_lshl_add_u64 v[226:227], vcc, 0, v[176:177]
	s_add_i32 m0, s17, 0xc000
	ds_read_b128 v[190:193], v188
	ds_read_b128 v[194:197], v188 offset:1024
	ds_read_b128 v[198:201], v188 offset:2048
	ds_read_b128 v[202:205], v188 offset:3072
	ds_read_b128 v[206:209], v188 offset:4096
	ds_read_b128 v[210:213], v188 offset:5120
	ds_read_b128 v[214:217], v188 offset:6144
	ds_read_b128 v[218:221], v188 offset:7168
	global_load_lds_dwordx4 v[226:227], off
	v_lshl_add_u64 v[226:227], vcc, 0, v[178:179]
	s_add_i32 m0, s17, 0xe000
	s_nop 0
	global_load_lds_dwordx4 v[226:227], off
	s_waitcnt vmcnt(8)
	s_waitcnt lgkmcnt(0)
	s_setprio 1
	s_barrier
	v_mfma_f32_16x16x32_bf16 v[148:151], v[36:39], v[190:193], v[148:151]
	v_mfma_f32_16x16x32_bf16 v[152:155], v[84:87], v[190:193], v[152:155]
	v_mfma_f32_16x16x32_bf16 v[128:131], v[36:39], v[198:201], v[128:131]
	v_mfma_f32_16x16x32_bf16 v[132:135], v[84:87], v[198:201], v[132:135]
	v_mfma_f32_16x16x32_bf16 v[108:111], v[36:39], v[206:209], v[108:111]
	v_mfma_f32_16x16x32_bf16 v[112:115], v[84:87], v[206:209], v[112:115]
	v_mfma_f32_16x16x32_bf16 v[88:91], v[36:39], v[214:217], v[88:91]
	v_mfma_f32_16x16x32_bf16 v[92:95], v[84:87], v[214:217], v[92:95]
	v_mfma_f32_16x16x32_bf16 v[148:151], v[56:59], v[194:197], v[148:151]
	v_mfma_f32_16x16x32_bf16 v[152:155], v[104:107], v[194:197], v[152:155]
	v_mfma_f32_16x16x32_bf16 v[128:131], v[56:59], v[202:205], v[128:131]
	v_mfma_f32_16x16x32_bf16 v[132:135], v[104:107], v[202:205], v[132:135]
	v_mfma_f32_16x16x32_bf16 v[108:111], v[56:59], v[210:213], v[108:111]
	v_mfma_f32_16x16x32_bf16 v[112:115], v[104:107], v[210:213], v[112:115]
	v_mfma_f32_16x16x32_bf16 v[88:91], v[56:59], v[218:221], v[88:91]
	v_mfma_f32_16x16x32_bf16 v[92:95], v[104:107], v[218:221], v[92:95]
	s_setprio 0
	s_setprio 1
	v_mfma_f32_16x16x32_bf16 v[140:143], v[124:127], v[190:193], v[140:143]
	v_mfma_f32_16x16x32_bf16 v[136:139], v[156:159], v[190:193], v[136:139]
	v_mfma_f32_16x16x32_bf16 v[120:123], v[124:127], v[198:201], v[120:123]
	v_mfma_f32_16x16x32_bf16 v[116:119], v[156:159], v[198:201], v[116:119]
	v_mfma_f32_16x16x32_bf16 v[100:103], v[124:127], v[206:209], v[100:103]
	v_mfma_f32_16x16x32_bf16 v[96:99], v[156:159], v[206:209], v[96:99]
	v_mfma_f32_16x16x32_bf16 v[80:83], v[124:127], v[214:217], v[80:83]
	v_mfma_f32_16x16x32_bf16 v[76:79], v[156:159], v[214:217], v[76:79]
	v_mfma_f32_16x16x32_bf16 v[140:143], v[144:147], v[194:197], v[140:143]
	v_mfma_f32_16x16x32_bf16 v[136:139], v[180:183], v[194:197], v[136:139]
	v_mfma_f32_16x16x32_bf16 v[120:123], v[144:147], v[202:205], v[120:123]
	v_mfma_f32_16x16x32_bf16 v[116:119], v[180:183], v[202:205], v[116:119]
	v_mfma_f32_16x16x32_bf16 v[100:103], v[144:147], v[210:213], v[100:103]
	v_mfma_f32_16x16x32_bf16 v[96:99], v[180:183], v[210:213], v[96:99]
	v_mfma_f32_16x16x32_bf16 v[80:83], v[144:147], v[218:221], v[80:83]
	v_mfma_f32_16x16x32_bf16 v[76:79], v[180:183], v[218:221], v[76:79]
	s_barrier
	s_setprio 0
	s_add_i32 s72, s95, s16
	v_lshl_add_u64 v[226:227], s[76:77], 0, v[164:165]
	s_mov_b32 m0, s72
	ds_read_b128 v[190:193], v188 offset:16384
	ds_read_b128 v[194:197], v188 offset:17408
	ds_read_b128 v[198:201], v188 offset:18432
	ds_read_b128 v[202:205], v188 offset:19456
	ds_read_b128 v[206:209], v188 offset:20480
	ds_read_b128 v[210:213], v188 offset:21504
	ds_read_b128 v[214:217], v188 offset:22528
	ds_read_b128 v[218:221], v188 offset:23552
	global_load_lds_dwordx4 v[226:227], off
	s_add_i32 m0, s72, 0x2000
	s_add_u32 s72, s76, 0x40000
	v_lshl_add_u64 v[228:229], s[76:77], 0, v[160:161]
	s_addc_u32 s73, s77, 0
	s_add_i32 s12, s12, s16
	global_load_lds_dwordx4 v[228:229], off
	v_lshl_add_u64 v[230:231], s[72:73], 0, v[164:165]
	s_mov_b32 m0, s12
	v_lshl_add_u64 v[232:233], s[78:79], 0, v[162:163]
	global_load_lds_dwordx4 v[230:231], off
	v_lshl_add_u64 v[230:231], s[72:73], 0, v[160:161]
	s_add_i32 m0, s12, 0x2000
	s_nop 0
	global_load_lds_dwordx4 v[230:231], off
	v_lshl_add_u64 v[230:231], s[78:79], 0, v[166:167]
	s_mov_b32 m0, s17
	s_nop 0
	global_load_lds_dwordx4 v[230:231], off
	s_mov_b32 m0, s46
	s_nop 0
	global_load_lds_dwordx4 v[232:233], off
	s_waitcnt vmcnt(8)
	s_waitcnt lgkmcnt(0)
	s_setprio 1
	s_barrier
	v_mfma_f32_16x16x32_bf16 v[68:71], v[36:39], v[190:193], v[68:71]
	v_mfma_f32_16x16x32_bf16 v[72:75], v[84:87], v[190:193], v[72:75]
	v_mfma_f32_16x16x32_bf16 v[48:51], v[36:39], v[198:201], v[48:51]
	v_mfma_f32_16x16x32_bf16 v[52:55], v[84:87], v[198:201], v[52:55]
	v_mfma_f32_16x16x32_bf16 v[28:31], v[36:39], v[206:209], v[28:31]
	v_mfma_f32_16x16x32_bf16 v[32:35], v[84:87], v[206:209], v[32:35]
	v_mfma_f32_16x16x32_bf16 v[10:13], v[36:39], v[214:217], v[10:13]
	v_mfma_f32_16x16x32_bf16 v[14:17], v[84:87], v[214:217], v[14:17]
	v_mfma_f32_16x16x32_bf16 v[68:71], v[56:59], v[194:197], v[68:71]
	v_mfma_f32_16x16x32_bf16 v[72:75], v[104:107], v[194:197], v[72:75]
	v_mfma_f32_16x16x32_bf16 v[48:51], v[56:59], v[202:205], v[48:51]
	v_mfma_f32_16x16x32_bf16 v[52:55], v[104:107], v[202:205], v[52:55]
	v_mfma_f32_16x16x32_bf16 v[28:31], v[56:59], v[210:213], v[28:31]
	v_mfma_f32_16x16x32_bf16 v[32:35], v[104:107], v[210:213], v[32:35]
	v_mfma_f32_16x16x32_bf16 v[10:13], v[56:59], v[218:221], v[10:13]
	v_mfma_f32_16x16x32_bf16 v[14:17], v[104:107], v[218:221], v[14:17]
	s_setprio 0
	s_setprio 1
	v_mfma_f32_16x16x32_bf16 v[44:47], v[124:127], v[198:201], v[44:47]
	v_mfma_f32_16x16x32_bf16 v[40:43], v[156:159], v[198:201], v[40:43]
	v_mfma_f32_16x16x32_bf16 v[22:25], v[124:127], v[206:209], v[22:25]
	v_mfma_f32_16x16x32_bf16 v[18:21], v[156:159], v[206:209], v[18:21]
	v_mfma_f32_16x16x32_bf16 v[2:5], v[124:127], v[214:217], v[2:5]
	v_mfma_f32_16x16x32_bf16 v[6:9], v[156:159], v[214:217], v[6:9]
	v_mfma_f32_16x16x32_bf16 v[36:39], v[124:127], v[190:193], v[64:67]
	v_mfma_f32_16x16x32_bf16 v[56:59], v[156:159], v[190:193], v[60:63]
	v_mfma_f32_16x16x32_bf16 v[44:47], v[144:147], v[202:205], v[44:47]
	v_mfma_f32_16x16x32_bf16 v[40:43], v[180:183], v[202:205], v[40:43]
	v_mfma_f32_16x16x32_bf16 v[22:25], v[144:147], v[210:213], v[22:25]
	v_mfma_f32_16x16x32_bf16 v[18:21], v[180:183], v[210:213], v[18:21]
	v_mfma_f32_16x16x32_bf16 v[2:5], v[144:147], v[218:221], v[2:5]
	v_mfma_f32_16x16x32_bf16 v[6:9], v[180:183], v[218:221], v[6:9]
	v_mfma_f32_16x16x32_bf16 v[36:39], v[144:147], v[194:197], v[36:39]
	v_mfma_f32_16x16x32_bf16 v[56:59], v[180:183], v[194:197], v[56:59]
	s_barrier
	s_setprio 0
	s_add_i32 s12, 0, 0x18000
	v_add_u32_e32 v26, s12, v186
	s_add_i32 s95, 0, 0x1c000
	ds_read_b128 v[60:63], v26
	ds_read_b128 v[64:67], v26 offset:1024
	ds_read_b128 v[84:87], v26 offset:2048
	ds_read_b128 v[104:107], v26 offset:3072
	v_add_u32_e32 v26, s95, v186
	ds_read_b128 v[124:127], v26
	ds_read_b128 v[144:147], v26 offset:1024
	ds_read_b128 v[156:159], v26 offset:2048
	ds_read_b128 v[180:183], v26 offset:3072
	s_add_u32 s72, s78, 0x160000
	s_addc_u32 s73, s79, 0
	s_mov_b32 m0, s47
	v_lshl_add_u64 v[234:235], s[72:73], 0, v[166:167]
	ds_read_b128 v[190:193], v188 offset:32768
	ds_read_b128 v[194:197], v188 offset:33792
	ds_read_b128 v[198:201], v188 offset:34816
	ds_read_b128 v[202:205], v188 offset:35840
	ds_read_b128 v[206:209], v188 offset:36864
	ds_read_b128 v[210:213], v188 offset:37888
	ds_read_b128 v[214:217], v188 offset:38912
	ds_read_b128 v[218:221], v188 offset:39936
	global_load_lds_dwordx4 v[234:235], off
	v_lshl_add_u64 v[234:235], s[72:73], 0, v[162:163]
	s_mov_b32 m0, s8
	s_nop 0
	global_load_lds_dwordx4 v[234:235], off
	s_waitcnt vmcnt(8)
	s_waitcnt lgkmcnt(0)
	s_setprio 1
	s_barrier
	v_mfma_f32_16x16x32_bf16 v[148:151], v[60:63], v[190:193], v[148:151]
	v_mfma_f32_16x16x32_bf16 v[152:155], v[84:87], v[190:193], v[152:155]
	v_mfma_f32_16x16x32_bf16 v[128:131], v[60:63], v[198:201], v[128:131]
	v_mfma_f32_16x16x32_bf16 v[132:135], v[84:87], v[198:201], v[132:135]
	v_mfma_f32_16x16x32_bf16 v[108:111], v[60:63], v[206:209], v[108:111]
	v_mfma_f32_16x16x32_bf16 v[112:115], v[84:87], v[206:209], v[112:115]
	v_mfma_f32_16x16x32_bf16 v[88:91], v[60:63], v[214:217], v[88:91]
	v_mfma_f32_16x16x32_bf16 v[92:95], v[84:87], v[214:217], v[92:95]
	v_mfma_f32_16x16x32_bf16 v[148:151], v[64:67], v[194:197], v[148:151]
	v_mfma_f32_16x16x32_bf16 v[152:155], v[104:107], v[194:197], v[152:155]
	v_mfma_f32_16x16x32_bf16 v[128:131], v[64:67], v[202:205], v[128:131]
	v_mfma_f32_16x16x32_bf16 v[132:135], v[104:107], v[202:205], v[132:135]
	v_mfma_f32_16x16x32_bf16 v[108:111], v[64:67], v[210:213], v[108:111]
	v_mfma_f32_16x16x32_bf16 v[112:115], v[104:107], v[210:213], v[112:115]
	v_mfma_f32_16x16x32_bf16 v[88:91], v[64:67], v[218:221], v[88:91]
	v_mfma_f32_16x16x32_bf16 v[92:95], v[104:107], v[218:221], v[92:95]
	s_setprio 0
	s_setprio 1
	v_mfma_f32_16x16x32_bf16 v[140:143], v[124:127], v[190:193], v[140:143]
	v_mfma_f32_16x16x32_bf16 v[136:139], v[156:159], v[190:193], v[136:139]
	v_mfma_f32_16x16x32_bf16 v[120:123], v[124:127], v[198:201], v[120:123]
	v_mfma_f32_16x16x32_bf16 v[116:119], v[156:159], v[198:201], v[116:119]
	v_mfma_f32_16x16x32_bf16 v[100:103], v[124:127], v[206:209], v[100:103]
	v_mfma_f32_16x16x32_bf16 v[96:99], v[156:159], v[206:209], v[96:99]
	v_mfma_f32_16x16x32_bf16 v[80:83], v[124:127], v[214:217], v[80:83]
	v_mfma_f32_16x16x32_bf16 v[76:79], v[156:159], v[214:217], v[76:79]
	v_mfma_f32_16x16x32_bf16 v[140:143], v[144:147], v[194:197], v[140:143]
	v_mfma_f32_16x16x32_bf16 v[136:139], v[180:183], v[194:197], v[136:139]
	v_mfma_f32_16x16x32_bf16 v[120:123], v[144:147], v[202:205], v[120:123]
	v_mfma_f32_16x16x32_bf16 v[116:119], v[180:183], v[202:205], v[116:119]
	v_mfma_f32_16x16x32_bf16 v[100:103], v[144:147], v[210:213], v[100:103]
	v_mfma_f32_16x16x32_bf16 v[96:99], v[180:183], v[210:213], v[96:99]
	v_mfma_f32_16x16x32_bf16 v[80:83], v[144:147], v[218:221], v[80:83]
	v_mfma_f32_16x16x32_bf16 v[76:79], v[180:183], v[218:221], v[76:79]
	s_barrier
	s_setprio 0
	s_add_i32 s12, s12, s16
	v_lshl_add_u64 v[226:227], v[226:227], 0, s[82:83]
	s_mov_b32 m0, s12
	ds_read_b128 v[190:193], v188 offset:49152
	ds_read_b128 v[194:197], v188 offset:50176
	ds_read_b128 v[198:201], v188 offset:51200
	ds_read_b128 v[202:205], v188 offset:52224
	ds_read_b128 v[206:209], v188 offset:53248
	ds_read_b128 v[210:213], v188 offset:54272
	ds_read_b128 v[214:217], v188 offset:55296
	ds_read_b128 v[218:221], v188 offset:56320
	global_load_lds_dwordx4 v[226:227], off
	s_add_i32 m0, s12, 0x2000
	s_add_u32 s72, s76, 0x40080
	v_lshl_add_u64 v[226:227], v[228:229], 0, s[82:83]
	s_addc_u32 s73, s77, 0
	s_add_i32 s12, s95, s16
	global_load_lds_dwordx4 v[226:227], off
	v_lshl_add_u64 v[226:227], s[72:73], 0, v[164:165]
	s_mov_b32 m0, s12
	s_nop 0
	global_load_lds_dwordx4 v[226:227], off
	v_lshl_add_u64 v[226:227], s[72:73], 0, v[160:161]
	s_add_i32 m0, s12, 0x2000
	s_nop 0
	global_load_lds_dwordx4 v[226:227], off
	v_lshl_add_u64 v[226:227], v[230:231], 0, s[82:83]
	s_mov_b32 m0, s22
	s_nop 0
	global_load_lds_dwordx4 v[226:227], off
	v_lshl_add_u64 v[226:227], v[232:233], 0, s[82:83]
	s_mov_b32 m0, s80
	s_nop 0
	global_load_lds_dwordx4 v[226:227], off
	s_waitcnt vmcnt(8)
	s_waitcnt lgkmcnt(0)
	s_setprio 1
	s_barrier
	v_mfma_f32_16x16x32_bf16 v[68:71], v[60:63], v[190:193], v[68:71]
	v_mfma_f32_16x16x32_bf16 v[72:75], v[84:87], v[190:193], v[72:75]
	v_mfma_f32_16x16x32_bf16 v[48:51], v[60:63], v[198:201], v[48:51]
	v_mfma_f32_16x16x32_bf16 v[52:55], v[84:87], v[198:201], v[52:55]
	v_mfma_f32_16x16x32_bf16 v[28:31], v[60:63], v[206:209], v[28:31]
	v_mfma_f32_16x16x32_bf16 v[32:35], v[84:87], v[206:209], v[32:35]
	v_mfma_f32_16x16x32_bf16 v[10:13], v[60:63], v[214:217], v[10:13]
	v_mfma_f32_16x16x32_bf16 v[14:17], v[84:87], v[214:217], v[14:17]
	v_mfma_f32_16x16x32_bf16 v[68:71], v[64:67], v[194:197], v[68:71]
	v_mfma_f32_16x16x32_bf16 v[72:75], v[104:107], v[194:197], v[72:75]
	v_mfma_f32_16x16x32_bf16 v[48:51], v[64:67], v[202:205], v[48:51]
	v_mfma_f32_16x16x32_bf16 v[52:55], v[104:107], v[202:205], v[52:55]
	v_mfma_f32_16x16x32_bf16 v[28:31], v[64:67], v[210:213], v[28:31]
	v_mfma_f32_16x16x32_bf16 v[32:35], v[104:107], v[210:213], v[32:35]
	v_mfma_f32_16x16x32_bf16 v[10:13], v[64:67], v[218:221], v[10:13]
	v_mfma_f32_16x16x32_bf16 v[14:17], v[104:107], v[218:221], v[14:17]
	s_setprio 0
	s_setprio 1
	v_mfma_f32_16x16x32_bf16 v[36:39], v[124:127], v[190:193], v[36:39]
	v_mfma_f32_16x16x32_bf16 v[64:67], v[144:147], v[194:197], v[36:39]
	v_mfma_f32_16x16x32_bf16 v[36:39], v[156:159], v[190:193], v[56:59]
	v_mfma_f32_16x16x32_bf16 v[60:63], v[180:183], v[194:197], v[36:39]
	v_mfma_f32_16x16x32_bf16 v[36:39], v[124:127], v[198:201], v[44:47]
	v_mfma_f32_16x16x32_bf16 v[44:47], v[144:147], v[202:205], v[36:39]
	v_mfma_f32_16x16x32_bf16 v[36:39], v[156:159], v[198:201], v[40:43]
	v_mfma_f32_16x16x32_bf16 v[22:25], v[124:127], v[206:209], v[22:25]
	v_mfma_f32_16x16x32_bf16 v[18:21], v[156:159], v[206:209], v[18:21]
	v_mfma_f32_16x16x32_bf16 v[2:5], v[124:127], v[214:217], v[2:5]
	v_mfma_f32_16x16x32_bf16 v[6:9], v[156:159], v[214:217], v[6:9]
	v_mfma_f32_16x16x32_bf16 v[40:43], v[180:183], v[202:205], v[36:39]
	v_mfma_f32_16x16x32_bf16 v[22:25], v[144:147], v[210:213], v[22:25]
	v_mfma_f32_16x16x32_bf16 v[18:21], v[180:183], v[210:213], v[18:21]
	v_mfma_f32_16x16x32_bf16 v[2:5], v[144:147], v[218:221], v[2:5]
	v_mfma_f32_16x16x32_bf16 v[6:9], v[180:183], v[218:221], v[6:9]
	s_barrier
	s_setprio 0
	s_add_i32 s93, s93, 2
	s_add_u32 vcc_lo, vcc_lo, 0x100
	s_addc_u32 vcc_hi, vcc_hi, 0
	s_add_u32 s84, s84, 0x100
	s_addc_u32 s85, s85, 0
	s_cmp_eq_u32 s93, 12
	s_cbranch_scc0 .Lti_nl
	s_cmp_lg_u32 s31, 3
	s_cbranch_scc1 .Lti_last
.Lti_nl:
	s_cmp_gt_u32 s93, 13
	s_cbranch_scc0 .LBB0_111
	s_branch .Lti_post
.Lti_last:
	s_add_u32 s72, vcc_lo, 0xffea0080
	s_addc_u32 s73, vcc_hi, -1
	s_add_i32 s95, 0, 0x10000
	s_cmp_eq_u32 s93, 12
	s_cselect_b32 s79, s1, s73
	s_cselect_b32 s78, s0, s72
	v_add_u32_e32 v26, s95, v186
	s_cselect_b32 s77, s89, s85
	s_cselect_b32 s76, s88, s84
	s_add_i32 s12, 0, 0x14000
	ds_read_b128 v[36:39], v26
	ds_read_b128 v[56:59], v26 offset:1024
	ds_read_b128 v[84:87], v26 offset:2048
	ds_read_b128 v[104:107], v26 offset:3072
	v_add_u32_e32 v26, s12, v186
	ds_read_b128 v[124:127], v26
	ds_read_b128 v[144:147], v26 offset:1024
	ds_read_b128 v[156:159], v26 offset:2048
	ds_read_b128 v[180:183], v26 offset:3072
	v_lshl_add_u64 v[226:227], vcc, 0, v[176:177]
	s_add_i32 m0, s17, 0xc000
	ds_read_b128 v[190:193], v188
	ds_read_b128 v[194:197], v188 offset:1024
	ds_read_b128 v[198:201], v188 offset:2048
	ds_read_b128 v[202:205], v188 offset:3072
	ds_read_b128 v[206:209], v188 offset:4096
	ds_read_b128 v[210:213], v188 offset:5120
	ds_read_b128 v[214:217], v188 offset:6144
	ds_read_b128 v[218:221], v188 offset:7168
	global_load_lds_dwordx4 v[226:227], off
	v_lshl_add_u64 v[226:227], vcc, 0, v[178:179]
	s_add_i32 m0, s17, 0xe000
	s_nop 0
	global_load_lds_dwordx4 v[226:227], off
	s_waitcnt vmcnt(8)
	s_waitcnt lgkmcnt(0)
	s_setprio 1
	s_barrier
	v_mfma_f32_16x16x32_bf16 v[148:151], v[36:39], v[190:193], v[148:151]
	v_mfma_f32_16x16x32_bf16 v[152:155], v[84:87], v[190:193], v[152:155]
	v_mfma_f32_16x16x32_bf16 v[128:131], v[36:39], v[198:201], v[128:131]
	v_mfma_f32_16x16x32_bf16 v[132:135], v[84:87], v[198:201], v[132:135]
	v_mfma_f32_16x16x32_bf16 v[108:111], v[36:39], v[206:209], v[108:111]
	v_mfma_f32_16x16x32_bf16 v[112:115], v[84:87], v[206:209], v[112:115]
	v_mfma_f32_16x16x32_bf16 v[88:91], v[36:39], v[214:217], v[88:91]
	v_mfma_f32_16x16x32_bf16 v[92:95], v[84:87], v[214:217], v[92:95]
	v_mfma_f32_16x16x32_bf16 v[148:151], v[56:59], v[194:197], v[148:151]
	v_mfma_f32_16x16x32_bf16 v[152:155], v[104:107], v[194:197], v[152:155]
	v_mfma_f32_16x16x32_bf16 v[128:131], v[56:59], v[202:205], v[128:131]
	v_mfma_f32_16x16x32_bf16 v[132:135], v[104:107], v[202:205], v[132:135]
	v_mfma_f32_16x16x32_bf16 v[108:111], v[56:59], v[210:213], v[108:111]
	v_mfma_f32_16x16x32_bf16 v[112:115], v[104:107], v[210:213], v[112:115]
	v_mfma_f32_16x16x32_bf16 v[88:91], v[56:59], v[218:221], v[88:91]
	v_mfma_f32_16x16x32_bf16 v[92:95], v[104:107], v[218:221], v[92:95]
	s_setprio 0
	s_setprio 1
	v_mfma_f32_16x16x32_bf16 v[140:143], v[124:127], v[190:193], v[140:143]
	v_mfma_f32_16x16x32_bf16 v[136:139], v[156:159], v[190:193], v[136:139]
	v_mfma_f32_16x16x32_bf16 v[120:123], v[124:127], v[198:201], v[120:123]
	v_mfma_f32_16x16x32_bf16 v[116:119], v[156:159], v[198:201], v[116:119]
	v_mfma_f32_16x16x32_bf16 v[100:103], v[124:127], v[206:209], v[100:103]
	v_mfma_f32_16x16x32_bf16 v[96:99], v[156:159], v[206:209], v[96:99]
	v_mfma_f32_16x16x32_bf16 v[80:83], v[124:127], v[214:217], v[80:83]
	v_mfma_f32_16x16x32_bf16 v[76:79], v[156:159], v[214:217], v[76:79]
	v_mfma_f32_16x16x32_bf16 v[140:143], v[144:147], v[194:197], v[140:143]
	v_mfma_f32_16x16x32_bf16 v[136:139], v[180:183], v[194:197], v[136:139]
	v_mfma_f32_16x16x32_bf16 v[120:123], v[144:147], v[202:205], v[120:123]
	v_mfma_f32_16x16x32_bf16 v[116:119], v[180:183], v[202:205], v[116:119]
	v_mfma_f32_16x16x32_bf16 v[100:103], v[144:147], v[210:213], v[100:103]
	v_mfma_f32_16x16x32_bf16 v[96:99], v[180:183], v[210:213], v[96:99]
	v_mfma_f32_16x16x32_bf16 v[80:83], v[144:147], v[218:221], v[80:83]
	v_mfma_f32_16x16x32_bf16 v[76:79], v[180:183], v[218:221], v[76:79]
	s_barrier
	s_setprio 0
	s_add_i32 s72, s95, s16
	v_lshl_add_u64 v[226:227], s[76:77], 0, v[164:165]
	s_mov_b32 m0, s72
	ds_read_b128 v[190:193], v188 offset:16384
	ds_read_b128 v[194:197], v188 offset:17408
	ds_read_b128 v[198:201], v188 offset:18432
	ds_read_b128 v[202:205], v188 offset:19456
	ds_read_b128 v[206:209], v188 offset:20480
	ds_read_b128 v[210:213], v188 offset:21504
	ds_read_b128 v[214:217], v188 offset:22528
	ds_read_b128 v[218:221], v188 offset:23552
	global_load_lds_dwordx4 v[226:227], off
	s_add_i32 m0, s72, 0x2000
	s_add_u32 s72, s76, 0x40000
	v_lshl_add_u64 v[228:229], s[76:77], 0, v[160:161]
	s_addc_u32 s73, s77, 0
	s_add_i32 s12, s12, s16
	global_load_lds_dwordx4 v[228:229], off
	v_lshl_add_u64 v[230:231], s[72:73], 0, v[164:165]
	s_mov_b32 m0, s12
	v_lshl_add_u64 v[232:233], s[78:79], 0, v[162:163]
	global_load_lds_dwordx4 v[230:231], off
	v_lshl_add_u64 v[230:231], s[72:73], 0, v[160:161]
	s_add_i32 m0, s12, 0x2000
	s_nop 0
	global_load_lds_dwordx4 v[230:231], off
	v_lshl_add_u64 v[230:231], s[78:79], 0, v[166:167]
	s_mov_b32 m0, s17
	s_nop 0
	global_load_lds_dwordx4 v[230:231], off
	s_mov_b32 m0, s46
	s_nop 0
	global_load_lds_dwordx4 v[232:233], off
	s_waitcnt vmcnt(8)
	s_waitcnt lgkmcnt(0)
	s_setprio 1
	s_barrier
	v_mfma_f32_16x16x32_bf16 v[68:71], v[36:39], v[190:193], v[68:71]
	v_mfma_f32_16x16x32_bf16 v[72:75], v[84:87], v[190:193], v[72:75]
	v_mfma_f32_16x16x32_bf16 v[48:51], v[36:39], v[198:201], v[48:51]
	v_mfma_f32_16x16x32_bf16 v[52:55], v[84:87], v[198:201], v[52:55]
	v_mfma_f32_16x16x32_bf16 v[28:31], v[36:39], v[206:209], v[28:31]
	v_mfma_f32_16x16x32_bf16 v[32:35], v[84:87], v[206:209], v[32:35]
	v_mfma_f32_16x16x32_bf16 v[10:13], v[36:39], v[214:217], v[10:13]
	v_mfma_f32_16x16x32_bf16 v[14:17], v[84:87], v[214:217], v[14:17]
	v_mfma_f32_16x16x32_bf16 v[68:71], v[56:59], v[194:197], v[68:71]
	v_mfma_f32_16x16x32_bf16 v[72:75], v[104:107], v[194:197], v[72:75]
	v_mfma_f32_16x16x32_bf16 v[48:51], v[56:59], v[202:205], v[48:51]
	v_mfma_f32_16x16x32_bf16 v[52:55], v[104:107], v[202:205], v[52:55]
	v_mfma_f32_16x16x32_bf16 v[28:31], v[56:59], v[210:213], v[28:31]
	v_mfma_f32_16x16x32_bf16 v[32:35], v[104:107], v[210:213], v[32:35]
	v_mfma_f32_16x16x32_bf16 v[10:13], v[56:59], v[218:221], v[10:13]
	v_mfma_f32_16x16x32_bf16 v[14:17], v[104:107], v[218:221], v[14:17]
	s_setprio 0
	s_setprio 1
	v_mfma_f32_16x16x32_bf16 v[44:47], v[124:127], v[198:201], v[44:47]
	v_mfma_f32_16x16x32_bf16 v[40:43], v[156:159], v[198:201], v[40:43]
	v_mfma_f32_16x16x32_bf16 v[22:25], v[124:127], v[206:209], v[22:25]
	v_mfma_f32_16x16x32_bf16 v[18:21], v[156:159], v[206:209], v[18:21]
	v_mfma_f32_16x16x32_bf16 v[2:5], v[124:127], v[214:217], v[2:5]
	v_mfma_f32_16x16x32_bf16 v[6:9], v[156:159], v[214:217], v[6:9]
	v_mfma_f32_16x16x32_bf16 v[36:39], v[124:127], v[190:193], v[64:67]
	v_mfma_f32_16x16x32_bf16 v[56:59], v[156:159], v[190:193], v[60:63]
	v_mfma_f32_16x16x32_bf16 v[44:47], v[144:147], v[202:205], v[44:47]
	v_mfma_f32_16x16x32_bf16 v[40:43], v[180:183], v[202:205], v[40:43]
	v_mfma_f32_16x16x32_bf16 v[22:25], v[144:147], v[210:213], v[22:25]
	v_mfma_f32_16x16x32_bf16 v[18:21], v[180:183], v[210:213], v[18:21]
	v_mfma_f32_16x16x32_bf16 v[2:5], v[144:147], v[218:221], v[2:5]
	v_mfma_f32_16x16x32_bf16 v[6:9], v[180:183], v[218:221], v[6:9]
	v_mfma_f32_16x16x32_bf16 v[36:39], v[144:147], v[194:197], v[36:39]
	v_mfma_f32_16x16x32_bf16 v[56:59], v[180:183], v[194:197], v[56:59]
	s_barrier
	s_setprio 0
	s_add_i32 s12, 0, 0x18000
	v_add_u32_e32 v26, s12, v186
	s_add_i32 s95, 0, 0x1c000
	ds_read_b128 v[60:63], v26
	ds_read_b128 v[64:67], v26 offset:1024
	ds_read_b128 v[84:87], v26 offset:2048
	ds_read_b128 v[104:107], v26 offset:3072
	v_add_u32_e32 v26, s95, v186
	ds_read_b128 v[124:127], v26
	ds_read_b128 v[144:147], v26 offset:1024
	ds_read_b128 v[156:159], v26 offset:2048
	ds_read_b128 v[180:183], v26 offset:3072
	s_add_u32 s72, s78, 0x160000
	s_addc_u32 s73, s79, 0
	s_mov_b32 m0, s47
	v_lshl_add_u64 v[234:235], s[72:73], 0, v[166:167]
	ds_read_b128 v[190:193], v188 offset:32768
	ds_read_b128 v[194:197], v188 offset:33792
	ds_read_b128 v[198:201], v188 offset:34816
	ds_read_b128 v[202:205], v188 offset:35840
	ds_read_b128 v[206:209], v188 offset:36864
	ds_read_b128 v[210:213], v188 offset:37888
	ds_read_b128 v[214:217], v188 offset:38912
	ds_read_b128 v[218:221], v188 offset:39936
	global_load_lds_dwordx4 v[234:235], off
	v_lshl_add_u64 v[234:235], s[72:73], 0, v[162:163]
	s_mov_b32 m0, s8
	s_nop 0
	global_load_lds_dwordx4 v[234:235], off
	s_waitcnt vmcnt(8)
	s_waitcnt lgkmcnt(0)
	s_setprio 1
	s_barrier
	v_mfma_f32_16x16x32_bf16 v[148:151], v[60:63], v[190:193], v[148:151]
	v_mfma_f32_16x16x32_bf16 v[152:155], v[84:87], v[190:193], v[152:155]
	v_mfma_f32_16x16x32_bf16 v[128:131], v[60:63], v[198:201], v[128:131]
	v_mfma_f32_16x16x32_bf16 v[132:135], v[84:87], v[198:201], v[132:135]
	v_mfma_f32_16x16x32_bf16 v[108:111], v[60:63], v[206:209], v[108:111]
	v_mfma_f32_16x16x32_bf16 v[112:115], v[84:87], v[206:209], v[112:115]
	v_mfma_f32_16x16x32_bf16 v[88:91], v[60:63], v[214:217], v[88:91]
	v_mfma_f32_16x16x32_bf16 v[92:95], v[84:87], v[214:217], v[92:95]
	v_mfma_f32_16x16x32_bf16 v[148:151], v[64:67], v[194:197], v[148:151]
	v_mfma_f32_16x16x32_bf16 v[152:155], v[104:107], v[194:197], v[152:155]
	v_mfma_f32_16x16x32_bf16 v[128:131], v[64:67], v[202:205], v[128:131]
	v_mfma_f32_16x16x32_bf16 v[132:135], v[104:107], v[202:205], v[132:135]
	v_mfma_f32_16x16x32_bf16 v[108:111], v[64:67], v[210:213], v[108:111]
	v_mfma_f32_16x16x32_bf16 v[112:115], v[104:107], v[210:213], v[112:115]
	v_mfma_f32_16x16x32_bf16 v[88:91], v[64:67], v[218:221], v[88:91]
	v_mfma_f32_16x16x32_bf16 v[92:95], v[104:107], v[218:221], v[92:95]
	s_setprio 0
	s_setprio 1
	v_mfma_f32_16x16x32_bf16 v[140:143], v[124:127], v[190:193], v[140:143]
	v_mfma_f32_16x16x32_bf16 v[136:139], v[156:159], v[190:193], v[136:139]
	v_mfma_f32_16x16x32_bf16 v[120:123], v[124:127], v[198:201], v[120:123]
	v_mfma_f32_16x16x32_bf16 v[116:119], v[156:159], v[198:201], v[116:119]
	v_mfma_f32_16x16x32_bf16 v[100:103], v[124:127], v[206:209], v[100:103]
	v_mfma_f32_16x16x32_bf16 v[96:99], v[156:159], v[206:209], v[96:99]
	v_mfma_f32_16x16x32_bf16 v[80:83], v[124:127], v[214:217], v[80:83]
	v_mfma_f32_16x16x32_bf16 v[76:79], v[156:159], v[214:217], v[76:79]
	v_mfma_f32_16x16x32_bf16 v[140:143], v[144:147], v[194:197], v[140:143]
	v_mfma_f32_16x16x32_bf16 v[136:139], v[180:183], v[194:197], v[136:139]
	v_mfma_f32_16x16x32_bf16 v[120:123], v[144:147], v[202:205], v[120:123]
	v_mfma_f32_16x16x32_bf16 v[116:119], v[180:183], v[202:205], v[116:119]
	v_mfma_f32_16x16x32_bf16 v[100:103], v[144:147], v[210:213], v[100:103]
	v_mfma_f32_16x16x32_bf16 v[96:99], v[180:183], v[210:213], v[96:99]
	v_mfma_f32_16x16x32_bf16 v[80:83], v[144:147], v[218:221], v[80:83]
	v_mfma_f32_16x16x32_bf16 v[76:79], v[180:183], v[218:221], v[76:79]
	s_barrier
	s_setprio 0
	s_add_i32 s12, s12, s16
	v_lshl_add_u64 v[226:227], v[226:227], 0, s[82:83]
	s_mov_b32 m0, s12
	ds_read_b128 v[190:193], v188 offset:49152
	ds_read_b128 v[194:197], v188 offset:50176
	ds_read_b128 v[198:201], v188 offset:51200
	ds_read_b128 v[202:205], v188 offset:52224
	ds_read_b128 v[206:209], v188 offset:53248
	ds_read_b128 v[210:213], v188 offset:54272
	ds_read_b128 v[214:217], v188 offset:55296
	ds_read_b128 v[218:221], v188 offset:56320
	s_and_b32 s98, s94, 7
	s_lshl_b32 s98, s98, 10
	v_lshl_add_u32 v238, v184, 2, s98
	v_add_u32_e32 v238, 0x20000, v238
	ds_read_b32 v242, v238
	ds_read_b32 v243, v238 offset:64
	ds_read_b32 v244, v238 offset:128
	ds_read_b32 v245, v238 offset:192
	ds_read_b32 v246, v238 offset:512
	ds_read_b32 v247, v238 offset:576
	ds_read_b32 v248, v238 offset:640
	ds_read_b32 v249, v238 offset:704
	global_load_lds_dwordx4 v[226:227], off
	s_add_i32 m0, s12, 0x2000
	s_add_u32 s72, s76, 0x40080
	v_lshl_add_u64 v[226:227], v[228:229], 0, s[82:83]
	s_addc_u32 s73, s77, 0
	s_add_i32 s12, s95, s16
	global_load_lds_dwordx4 v[226:227], off
	v_lshl_add_u64 v[226:227], s[72:73], 0, v[164:165]
	s_mov_b32 m0, s12
	s_nop 0
	global_load_lds_dwordx4 v[226:227], off
	v_lshl_add_u64 v[226:227], s[72:73], 0, v[160:161]
	s_add_i32 m0, s12, 0x2000
	s_nop 0
	global_load_lds_dwordx4 v[226:227], off
	v_lshl_add_u64 v[226:227], v[230:231], 0, s[82:83]
	s_mov_b32 m0, s22
	s_nop 0
	global_load_lds_dwordx4 v[226:227], off
	v_lshl_add_u64 v[226:227], v[232:233], 0, s[82:83]
	s_mov_b32 m0, s80
	s_nop 0
	global_load_lds_dwordx4 v[226:227], off
	s_mul_i32 s98, s94, 0x2c0000
	s_mul_hi_i32 s99, s94, 0x2c0000
	s_add_u32 s98, s19, s98
	s_addc_u32 s99, s25, s99
	s_lshl_b32 s72, s30, 9
	s_add_u32 s98, s98, s72
	s_addc_u32 s99, s99, 0
	v_mul_lo_u32 v236, v184, s7
	v_mov_b32_e32 v237, 0
	v_or_b32_e32 v236, v236, v187
	s_waitcnt vmcnt(8)
	s_waitcnt lgkmcnt(0)
	s_setprio 1
	s_barrier
	v_mfma_f32_16x16x32_bf16 v[68:71], v[60:63], v[190:193], v[68:71]
	v_mov_b32_e32 v226, v242
	v_mov_b32_e32 v228, v243
	v_mov_b32_e32 v230, v244
	v_mfma_f32_16x16x32_bf16 v[72:75], v[84:87], v[190:193], v[72:75]
	v_mov_b32_e32 v232, v245
	v_pk_mul_f32 v[148:149], v[148:149], v[226:227] op_sel_hi:[1,0]
	v_pk_mul_f32 v[150:151], v[150:151], v[226:227] op_sel_hi:[1,0]
	v_mfma_f32_16x16x32_bf16 v[48:51], v[60:63], v[198:201], v[48:51]
	v_pk_mul_f32 v[152:153], v[152:153], v[226:227] op_sel_hi:[1,0]
	v_pk_mul_f32 v[154:155], v[154:155], v[226:227] op_sel_hi:[1,0]
	v_pk_mul_f32 v[140:141], v[140:141], v[226:227] op_sel_hi:[1,0]
	v_mfma_f32_16x16x32_bf16 v[52:55], v[84:87], v[198:201], v[52:55]
	v_pk_mul_f32 v[142:143], v[142:143], v[226:227] op_sel_hi:[1,0]
	v_pk_mul_f32 v[136:137], v[136:137], v[226:227] op_sel_hi:[1,0]
	v_pk_mul_f32 v[138:139], v[138:139], v[226:227] op_sel_hi:[1,0]
	v_mfma_f32_16x16x32_bf16 v[28:31], v[60:63], v[206:209], v[28:31]
	v_cvt_pk_bf16_f32 v148, v148, v149
	v_cvt_pk_bf16_f32 v149, v150, v151
	v_cvt_pk_bf16_f32 v150, v152, v153
	v_mfma_f32_16x16x32_bf16 v[32:35], v[84:87], v[206:209], v[32:35]
	v_cvt_pk_bf16_f32 v151, v154, v155
	global_store_dwordx4 v236, v[148:151], s[98:99]
	v_cvt_pk_bf16_f32 v140, v140, v141
	v_mfma_f32_16x16x32_bf16 v[10:13], v[60:63], v[214:217], v[10:13]
	v_cvt_pk_bf16_f32 v141, v142, v143
	v_cvt_pk_bf16_f32 v142, v136, v137
	v_cvt_pk_bf16_f32 v143, v138, v139
	v_mfma_f32_16x16x32_bf16 v[14:17], v[84:87], v[214:217], v[14:17]
	global_store_dwordx4 v236, v[140:143], s[98:99] offset:256
	s_add_u32 s98, s98, 0x2c000
	s_addc_u32 s99, s99, 0
	v_mfma_f32_16x16x32_bf16 v[68:71], v[64:67], v[194:197], v[68:71]
	v_pk_mul_f32 v[128:129], v[128:129], v[228:229] op_sel_hi:[1,0]
	v_pk_mul_f32 v[130:131], v[130:131], v[228:229] op_sel_hi:[1,0]
	v_pk_mul_f32 v[132:133], v[132:133], v[228:229] op_sel_hi:[1,0]
	v_mfma_f32_16x16x32_bf16 v[72:75], v[104:107], v[194:197], v[72:75]
	v_pk_mul_f32 v[134:135], v[134:135], v[228:229] op_sel_hi:[1,0]
	v_pk_mul_f32 v[120:121], v[120:121], v[228:229] op_sel_hi:[1,0]
	v_pk_mul_f32 v[122:123], v[122:123], v[228:229] op_sel_hi:[1,0]
	v_mfma_f32_16x16x32_bf16 v[48:51], v[64:67], v[202:205], v[48:51]
	v_pk_mul_f32 v[116:117], v[116:117], v[228:229] op_sel_hi:[1,0]
	v_pk_mul_f32 v[118:119], v[118:119], v[228:229] op_sel_hi:[1,0]
	v_cvt_pk_bf16_f32 v128, v128, v129
	v_mfma_f32_16x16x32_bf16 v[52:55], v[104:107], v[202:205], v[52:55]
	v_cvt_pk_bf16_f32 v129, v130, v131
	v_cvt_pk_bf16_f32 v130, v132, v133
	v_cvt_pk_bf16_f32 v131, v134, v135
	v_mfma_f32_16x16x32_bf16 v[28:31], v[64:67], v[210:213], v[28:31]
	global_store_dwordx4 v236, v[128:131], s[98:99]
	v_cvt_pk_bf16_f32 v120, v120, v121
	v_cvt_pk_bf16_f32 v121, v122, v123
	v_mfma_f32_16x16x32_bf16 v[32:35], v[104:107], v[210:213], v[32:35]
	v_cvt_pk_bf16_f32 v122, v116, v117
	v_cvt_pk_bf16_f32 v123, v118, v119
	global_store_dwordx4 v236, v[120:123], s[98:99] offset:256
	v_mfma_f32_16x16x32_bf16 v[10:13], v[64:67], v[218:221], v[10:13]
	s_add_u32 s98, s98, 0x2c000
	s_addc_u32 s99, s99, 0
	v_pk_mul_f32 v[108:109], v[108:109], v[230:231] op_sel_hi:[1,0]
	v_mfma_f32_16x16x32_bf16 v[14:17], v[104:107], v[218:221], v[14:17]
	v_pk_mul_f32 v[110:111], v[110:111], v[230:231] op_sel_hi:[1,0]
	v_pk_mul_f32 v[112:113], v[112:113], v[230:231] op_sel_hi:[1,0]
	v_pk_mul_f32 v[114:115], v[114:115], v[230:231] op_sel_hi:[1,0]
	s_setprio 0
	s_setprio 1
	v_mfma_f32_16x16x32_bf16 v[36:39], v[124:127], v[190:193], v[36:39]
	v_pk_mul_f32 v[100:101], v[100:101], v[230:231] op_sel_hi:[1,0]
	v_pk_mul_f32 v[102:103], v[102:103], v[230:231] op_sel_hi:[1,0]
	v_pk_mul_f32 v[96:97], v[96:97], v[230:231] op_sel_hi:[1,0]
	v_mfma_f32_16x16x32_bf16 v[64:67], v[144:147], v[194:197], v[36:39]
	v_pk_mul_f32 v[98:99], v[98:99], v[230:231] op_sel_hi:[1,0]
	v_cvt_pk_bf16_f32 v108, v108, v109
	v_cvt_pk_bf16_f32 v109, v110, v111
	v_mfma_f32_16x16x32_bf16 v[36:39], v[156:159], v[190:193], v[56:59]
	v_cvt_pk_bf16_f32 v110, v112, v113
	v_cvt_pk_bf16_f32 v111, v114, v115
	v_mfma_f32_16x16x32_bf16 v[60:63], v[180:183], v[194:197], v[36:39]
	global_store_dwordx4 v236, v[108:111], s[98:99]
	v_cvt_pk_bf16_f32 v100, v100, v101
	v_mfma_f32_16x16x32_bf16 v[36:39], v[124:127], v[198:201], v[44:47]
	v_cvt_pk_bf16_f32 v101, v102, v103
	v_cvt_pk_bf16_f32 v102, v96, v97
	v_mfma_f32_16x16x32_bf16 v[44:47], v[144:147], v[202:205], v[36:39]
	v_cvt_pk_bf16_f32 v103, v98, v99
	global_store_dwordx4 v236, v[100:103], s[98:99] offset:256
	v_mfma_f32_16x16x32_bf16 v[36:39], v[156:159], v[198:201], v[40:43]
	s_add_u32 s98, s98, 0x2c000
	s_addc_u32 s99, s99, 0
	v_mfma_f32_16x16x32_bf16 v[22:25], v[124:127], v[206:209], v[22:25]
	v_pk_mul_f32 v[88:89], v[88:89], v[232:233] op_sel_hi:[1,0]
	v_pk_mul_f32 v[90:91], v[90:91], v[232:233] op_sel_hi:[1,0]
	v_mfma_f32_16x16x32_bf16 v[18:21], v[156:159], v[206:209], v[18:21]
	v_pk_mul_f32 v[92:93], v[92:93], v[232:233] op_sel_hi:[1,0]
	v_pk_mul_f32 v[94:95], v[94:95], v[232:233] op_sel_hi:[1,0]
	v_mfma_f32_16x16x32_bf16 v[2:5], v[124:127], v[214:217], v[2:5]
	v_pk_mul_f32 v[80:81], v[80:81], v[232:233] op_sel_hi:[1,0]
	v_pk_mul_f32 v[82:83], v[82:83], v[232:233] op_sel_hi:[1,0]
	v_mfma_f32_16x16x32_bf16 v[6:9], v[156:159], v[214:217], v[6:9]
	v_pk_mul_f32 v[76:77], v[76:77], v[232:233] op_sel_hi:[1,0]
	v_pk_mul_f32 v[78:79], v[78:79], v[232:233] op_sel_hi:[1,0]
	v_mfma_f32_16x16x32_bf16 v[40:43], v[180:183], v[202:205], v[36:39]
	v_cvt_pk_bf16_f32 v88, v88, v89
	v_cvt_pk_bf16_f32 v89, v90, v91
	v_mfma_f32_16x16x32_bf16 v[22:25], v[144:147], v[210:213], v[22:25]
	v_cvt_pk_bf16_f32 v90, v92, v93
	v_cvt_pk_bf16_f32 v91, v94, v95
	v_mfma_f32_16x16x32_bf16 v[18:21], v[180:183], v[210:213], v[18:21]
	global_store_dwordx4 v236, v[88:91], s[98:99]
	v_cvt_pk_bf16_f32 v80, v80, v81
	v_mfma_f32_16x16x32_bf16 v[2:5], v[144:147], v[218:221], v[2:5]
	v_cvt_pk_bf16_f32 v81, v82, v83
	v_cvt_pk_bf16_f32 v82, v76, v77
	v_mfma_f32_16x16x32_bf16 v[6:9], v[180:183], v[218:221], v[6:9]
	v_cvt_pk_bf16_f32 v83, v78, v79
	global_store_dwordx4 v236, v[80:83], s[98:99] offset:256
	s_barrier
	s_setprio 0
	s_add_i32 s93, s93, 2
	s_add_u32 vcc_lo, vcc_lo, 0x100
	s_addc_u32 vcc_hi, vcc_hi, 0
	s_add_u32 s84, s84, 0x100
	s_addc_u32 s85, s85, 0
	s_and_b64 vcc, exec, s[60:61]
	s_cbranch_vccz .Lti_nb
	s_barrier
.Lti_nb:
	s_sub_u32 s98, s98, 0x84000
	s_subb_u32 s99, s99, 0
	v_lshl_add_u64 v[140:141], s[98:99], 0, v[236:237]
	v_lshlrev_b32_e32 v26, 6, v184
	v_mov_b32_e32 v181, v184
	s_mov_b64 s[0:1], -1
	s_branch .LBB0_154
.Lti_post:
	s_and_b64 vcc, exec, s[60:61]
	s_cbranch_vccz .LBB0_114
	s_barrier
